# overlap v6: v4 plus group-0 published as soon as complete, recurrence polls one chunk ahead without cache invalidate
# baseline (speedup 1.0000x reference)
.LBB0_131:
.Lsig_check:
	s_cmp_gt_u32 s98, 15
	s_cbranch_scc1 .Lsig_end
	s_cmp_lg_u64 s[4:5], 0
	s_cbranch_scc1 .Lsig_last
	s_add_u32 s99, s98, 1
	s_lshl_b32 s99, s99, 8
	s_sub_u32 s99, s99, 1
	s_mul_i32 s99, s99, 0xaaab
	s_lshr_b32 s99, s99, 23
	s_add_u32 s99, s99, 2
	s_cmp_eq_u32 s98, 0
	s_cbranch_scc0 .Lsig_norm
	s_sub_u32 s99, s99, 1
	s_cmp_ge_u32 s35, s99
	s_cbranch_scc0 .Lsig_end
	s_branch .Lsig_last
.Lsig_norm:
	s_cmp_ge_u32 s35, s99
	s_cbranch_scc0 .Lsig_end
	s_waitcnt vmcnt(24)
	s_branch .Lsig_go

.Lhs_chk_g0:
	s_waitcnt vmcnt(0)
	v_readfirstlane_b32 s100, v254
	s_cmp_ge_u32 s100, 0xc0
	s_cbranch_scc1 .Lhs_join_g0
	s_sleep 4
	s_add_u32 s99, s99, 1
	s_cmp_lt_u32 s99, 0x8000
	s_cbranch_scc1 .Lhs_g0

.LBB0_472:
	s_and_b32 s98, s71, 7
	s_cmp_gt_u32 s98, 1
	s_cbranch_scc1 .Lhw_skip
	s_cmp_lt_u32 s71, 2
	s_cbranch_scc1 .Lhw_skip
	s_lshr_b32 s99, s71, 3
	s_sub_u32 s99, 16, s99
	s_lshl_b32 s99, s99, 6
	s_add_u32 s99, s99, 0x3800
	v_mov_b32_e32 v253, s99
	s_cmp_eq_u32 s98, 0
	s_cbranch_scc1 .Lhw_wait
	v_readfirstlane_b32 s99, v208
	s_lshr_b32 s99, s99, 6
	s_cmp_lg_u32 s99, 0
	s_cbranch_scc1 .Lhw_skip
	global_load_dword v254, v253, s[74:75] sc1
	s_branch .Lhw_skip
.Lhw_wait:
	v_readfirstlane_b32 s99, v208
	s_lshr_b32 s99, s99, 6
	s_cmp_lg_u32 s99, 0
	s_cbranch_scc1 .Lhs_join_gn
	s_mov_b32 s99, 0
	s_branch .Lhs_chk_gn
